# attention: reference subtracted on the VALU again (4 fewer MFMAs per key tile), sum-based rescale check kept
# baseline (speedup 1.0000x reference)
.Lat_noprio:
	v_mov_b32_e32 v96, 0
	v_mov_b32_e32 v97, 0
	v_mov_b32_e32 v98, 0
	v_mov_b32_e32 v99, 0
	v_mov_b32_e32 v100, 0
	v_mov_b32_e32 v101, 0
	v_mov_b32_e32 v102, 0
	v_mov_b32_e32 v103, 0
	v_mov_b32_e32 v112, 0
	v_mov_b32_e32 v113, 0
	v_mov_b32_e32 v114, 0
	v_mov_b32_e32 v115, 0
	v_mov_b32_e32 v116, 0
	v_mov_b32_e32 v117, 0
	v_mov_b32_e32 v118, 0
	v_mov_b32_e32 v119, 0
	v_sub_u32_e32 v228, 1, v192
	v_mul_u32_u24_e32 v228, 0xffff, v228
	v_and_b32_e32 v240, 0x3f80, v228
	v_mov_b32_e32 v241, 0
	v_mov_b32_e32 v242, 0
	v_mov_b32_e32 v243, 0
	v_mov_b32_e32 v245, 0
	v_mov_b32_e32 v246, 0
	v_mov_b32_e32 v247, 0
	v_mov_b32_e32 v249, 0
	v_mov_b32_e32 v250, 0
	v_mov_b32_e32 v251, 0
	v_add3_u32 v224, s34, v183, v128
	ds_read_b128 v[212:215], v224 offset:0
	ds_read_b128 v[216:219], v224 offset:32
	ds_read_b128 v[220:223], v224 offset:64
	s_waitcnt lgkmcnt(2)
	v_mfma_f32_32x32x16_bf16 v[64:79], v[212:215], v[130:133], 0
	v_mfma_f32_32x32x16_bf16 v[80:95], v[212:215], v[138:141], 0
	ds_read_b128 v[212:215], v224 offset:96
	s_waitcnt lgkmcnt(2)
	v_mfma_f32_32x32x16_bf16 v[64:79], v[216:219], v[134:137], v[64:79]
	v_mfma_f32_32x32x16_bf16 v[80:95], v[216:219], v[142:145], v[80:95]
	ds_read_b128 v[216:219], v224 offset:128
	s_waitcnt lgkmcnt(2)
	v_mfma_f32_32x32x16_bf16 v[64:79], v[220:223], v[146:149], v[64:79]
	v_mfma_f32_32x32x16_bf16 v[80:95], v[220:223], v[154:157], v[80:95]
	ds_read_b128 v[220:223], v224 offset:160
	s_waitcnt lgkmcnt(2)
	v_mfma_f32_32x32x16_bf16 v[64:79], v[212:215], v[150:153], v[64:79]
	v_mfma_f32_32x32x16_bf16 v[80:95], v[212:215], v[158:161], v[80:95]
	s_waitcnt lgkmcnt(1)
	v_mfma_f32_32x32x16_bf16 v[64:79], v[216:219], v[162:165], v[64:79]
	v_mfma_f32_32x32x16_bf16 v[80:95], v[216:219], v[170:173], v[80:95]
	s_waitcnt lgkmcnt(0)
	v_mfma_f32_32x32x16_bf16 v[64:79], v[220:223], v[166:169], v[64:79]
	v_mfma_f32_32x32x16_bf16 v[80:95], v[220:223], v[174:177], v[80:95]
	s_nop 15
	s_nop 3
	v_max3_f32 v226, v64, v65, v66
	v_max3_f32 v227, v67, v68, v69
	v_max3_f32 v226, v226, v70, v71
	v_max3_f32 v227, v227, v72, v73
	v_max3_f32 v226, v226, v74, v75
	v_max3_f32 v227, v227, v76, v77
	v_max3_f32 v226, v226, v78, v79
	v_max_f32_e32 v226, v226, v227
	v_mov_b32_e32 v227, v226
	s_nop 1
	v_permlane32_swap_b32_e32 v226, v227
	v_max_f32_e32 v226, v226, v227
	v_cvt_pk_bf16_f32 v227, v226, v226
	v_and_b32_e32 v194, 0xffff0000, v227
	v_max3_f32 v236, v80, v81, v82
	v_max3_f32 v237, v83, v84, v85
	v_max3_f32 v236, v236, v86, v87
	v_max3_f32 v237, v237, v88, v89
	v_max3_f32 v236, v236, v90, v91
	v_max3_f32 v237, v237, v92, v93
	v_max3_f32 v236, v236, v94, v95
	v_max_f32_e32 v236, v236, v237
	v_mov_b32_e32 v237, v236
	s_nop 1
	v_permlane32_swap_b32_e32 v236, v237
	v_max_f32_e32 v236, v236, v237
	v_cvt_pk_bf16_f32 v237, v236, v236
	v_and_b32_e32 v195, 0xffff0000, v237
	v_add3_u32 v225, s34, v187, v128
	ds_read_b128 v[196:199], v225 offset:13376
	ds_read_b128 v[200:203], v225 offset:17984
	ds_read_b128 v[204:207], v225 offset:13408
	ds_read_b128 v[208:211], v225 offset:18016
	s_nop 7
	s_nop 3
.Lat_loop:
	v_add3_u32 v224, s34, v183, v128
	ds_read_b128 v[212:215], v224 offset:6656
	ds_read_b128 v[216:219], v224 offset:6688
	ds_read_b128 v[220:223], v224 offset:6720
	s_waitcnt lgkmcnt(6)
	v_mfma_f32_32x32x16_bf16 v[16:31], v[196:199], v[96:99], v[16:31]
	v_sub_f32_e32 v64, v64, v194
	v_sub_f32_e32 v65, v65, v194
	v_sub_f32_e32 v66, v66, v194
	v_sub_f32_e32 v67, v67, v194
	s_waitcnt lgkmcnt(5)
	v_mfma_f32_32x32x16_bf16 v[48:63], v[200:203], v[96:99], v[48:63]
	v_exp_f32_e32 v64, v64
	v_exp_f32_e32 v65, v65
	v_sub_f32_e32 v68, v68, v194
	v_sub_f32_e32 v69, v69, v194
	s_waitcnt lgkmcnt(4)
	v_mfma_f32_32x32x16_bf16 v[16:31], v[204:207], v[100:103], v[16:31]
	v_exp_f32_e32 v66, v66
	v_exp_f32_e32 v67, v67
	v_sub_f32_e32 v70, v70, v194
	v_sub_f32_e32 v71, v71, v194
	s_waitcnt lgkmcnt(3)
	v_mfma_f32_32x32x16_bf16 v[48:63], v[208:211], v[100:103], v[48:63]
	v_exp_f32_e32 v68, v68
	v_exp_f32_e32 v69, v69
	v_add_f32_e32 v230, v64, v65
	v_sub_f32_e32 v72, v72, v194
	v_sub_f32_e32 v73, v73, v194
	v_exp_f32_e32 v70, v70
	v_mfma_f32_32x32x16_bf16 v[32:47], v[196:199], v[112:115], v[32:47]
	v_exp_f32_e32 v71, v71
	v_add_f32_e32 v231, v66, v67
	v_sub_f32_e32 v74, v74, v194
	v_sub_f32_e32 v75, v75, v194
	v_mfma_f32_32x32x16_bf16 v[0:15], v[200:203], v[112:115], v[0:15]
	v_exp_f32_e32 v72, v72
	v_exp_f32_e32 v73, v73
	v_add_f32_e32 v230, v230, v68
	v_add_f32_e32 v231, v231, v69
	v_mfma_f32_32x32x16_bf16 v[32:47], v[204:207], v[116:119], v[32:47]
	v_sub_f32_e32 v76, v76, v194
	v_sub_f32_e32 v77, v77, v194
	v_exp_f32_e32 v74, v74
	v_exp_f32_e32 v75, v75
	v_mfma_f32_32x32x16_bf16 v[0:15], v[208:211], v[116:119], v[0:15]
	v_add_f32_e32 v230, v230, v70
	v_add3_u32 v225, s34, v187, v128
	ds_read_b128 v[196:199], v225 offset:13312
	ds_read_b128 v[200:203], v225 offset:17920
	ds_read_b128 v[204:207], v225 offset:13344
	ds_read_b128 v[208:211], v225 offset:17952
	v_add_f32_e32 v231, v231, v71
	v_sub_f32_e32 v78, v78, v194
	v_sub_f32_e32 v79, v79, v194
	v_exp_f32_e32 v76, v76
	v_exp_f32_e32 v77, v77
	v_add_f32_e32 v230, v230, v72
	v_add_f32_e32 v231, v231, v73
	v_exp_f32_e32 v78, v78
	v_exp_f32_e32 v79, v79
	v_add_f32_e32 v230, v230, v74
	v_add_f32_e32 v231, v231, v75
	v_add_f32_e32 v230, v230, v76
	v_add_f32_e32 v231, v231, v77
	v_add_f32_e32 v230, v230, v78
	v_add_f32_e32 v231, v231, v79
	v_add_f32_e32 v230, v230, v231
	v_cmp_lt_f32_e32 vcc, 0x45800000, v230
	s_cbranch_vccnz .Lat_resc_aE
; #define LAS __attribute__((address_space(3)))
; __device__ __forceinline__ void attn_unit2(LAS unsigned char* lds, const bf16_t* __restrict__ Q, const bf16_t* __restrict__ KN, const bf16_t* __restrict__ KPE, ...
;     ...
;         for (int ds = 0; ds < 6; ++ds) {
;             const bf16x8 k0 = *(const LAS bf16x8*)(ka + ds * 32);
;             const bf16x8 k1 = *(const LAS bf16x8*)(ka + 32 * KROW + ds * 32);
;             sa0 = __builtin_amdgcn_mfma_f32_32x32x16_bf16(k0, qa[ds], sa0, 0, 0, 0);
;             sa1 = __builtin_amdgcn_mfma_f32_32x32x16_bf16(k1, qa[ds], sa1, 0, 0, 0);
;             sb0 = __builtin_amdgcn_mfma_f32_32x32x16_bf16(k0, qb[ds], sb0, 0, 0, 0);
;             sb1 = __builtin_amdgcn_mfma_f32_32x32x16_bf16(k1, qb[ds], sb1, 0, 0, 0);
;         }
.Lat_back_aE:
	v_add_f32_e32 v191, v191, v230
	s_waitcnt lgkmcnt(6)
	v_mfma_f32_32x32x16_bf16 v[96:111], v[212:215], v[130:133], 0
	v_cvt_pk_bf16_f32 v64, v64, v65
	v_cvt_pk_bf16_f32 v65, v66, v67
	v_cvt_pk_bf16_f32 v66, v68, v69
	v_cvt_pk_bf16_f32 v67, v70, v71
	v_cvt_pk_bf16_f32 v68, v72, v73
	v_cvt_pk_bf16_f32 v69, v74, v75
	v_mfma_f32_32x32x16_bf16 v[112:127], v[212:215], v[138:141], 0
	ds_read_b128 v[212:215], v224 offset:6752
	v_cvt_pk_bf16_f32 v70, v76, v77
	v_cvt_pk_bf16_f32 v71, v78, v79
	v_sub_f32_e32 v80, v80, v195
	v_sub_f32_e32 v81, v81, v195
	v_sub_f32_e32 v82, v82, v195
	s_waitcnt lgkmcnt(6)
	v_mfma_f32_32x32x16_bf16 v[96:111], v[216:219], v[134:137], v[96:111]
	v_sub_f32_e32 v83, v83, v195
	v_exp_f32_e32 v80, v80
	v_exp_f32_e32 v81, v81
	v_sub_f32_e32 v84, v84, v195
	v_sub_f32_e32 v85, v85, v195
	v_exp_f32_e32 v82, v82
	v_mfma_f32_32x32x16_bf16 v[112:127], v[216:219], v[142:145], v[112:127]
	ds_read_b128 v[216:219], v224 offset:6784
	v_exp_f32_e32 v83, v83
	v_sub_f32_e32 v86, v86, v195
	v_sub_f32_e32 v87, v87, v195
	v_exp_f32_e32 v84, v84
	v_exp_f32_e32 v85, v85
	v_add_f32_e32 v230, v80, v81
	s_waitcnt lgkmcnt(6)
	v_mfma_f32_32x32x16_bf16 v[96:111], v[220:223], v[146:149], v[96:111]
	v_sub_f32_e32 v88, v88, v195
	v_sub_f32_e32 v89, v89, v195
	v_exp_f32_e32 v86, v86
	v_exp_f32_e32 v87, v87
	v_add_f32_e32 v231, v82, v83
	v_mfma_f32_32x32x16_bf16 v[112:127], v[220:223], v[154:157], v[112:127]
	ds_read_b128 v[220:223], v224 offset:6816
	v_sub_f32_e32 v90, v90, v195
	v_sub_f32_e32 v91, v91, v195
	v_exp_f32_e32 v88, v88
	v_exp_f32_e32 v89, v89
	v_add_f32_e32 v230, v230, v84
	v_add_f32_e32 v231, v231, v85
	s_waitcnt lgkmcnt(2)
	v_mfma_f32_32x32x16_bf16 v[96:111], v[212:215], v[150:153], v[96:111]
	v_sub_f32_e32 v92, v92, v195
	v_sub_f32_e32 v93, v93, v195
	v_exp_f32_e32 v90, v90
	v_exp_f32_e32 v91, v91
	v_add_f32_e32 v230, v230, v86
	v_mfma_f32_32x32x16_bf16 v[112:127], v[212:215], v[158:161], v[112:127]
	v_add_f32_e32 v231, v231, v87
	v_sub_f32_e32 v94, v94, v195
	v_sub_f32_e32 v95, v95, v195
	v_exp_f32_e32 v92, v92
	v_exp_f32_e32 v93, v93
	v_add_f32_e32 v230, v230, v88
	s_waitcnt lgkmcnt(1)
	v_mfma_f32_32x32x16_bf16 v[96:111], v[216:219], v[162:165], v[96:111]
	v_add_f32_e32 v231, v231, v89
	v_exp_f32_e32 v94, v94
	v_exp_f32_e32 v95, v95
	v_add_f32_e32 v230, v230, v90
	v_add_f32_e32 v231, v231, v91
	v_add_f32_e32 v230, v230, v92
	v_mfma_f32_32x32x16_bf16 v[112:127], v[216:219], v[170:173], v[112:127]
	v_add_f32_e32 v231, v231, v93
	v_add_f32_e32 v230, v230, v94
	v_add_f32_e32 v231, v231, v95
	v_add_f32_e32 v230, v230, v231
	v_cmp_lt_f32_e32 vcc, 0x45800000, v230
	s_cbranch_vccnz .Lat_resc_bE
.Lat_back_bE:
	s_waitcnt lgkmcnt(0)
	v_mfma_f32_32x32x16_bf16 v[96:111], v[220:223], v[166:169], v[96:111]
	v_add_f32_e32 v193, v193, v230
	v_cvt_pk_bf16_f32 v80, v80, v81
	v_cvt_pk_bf16_f32 v81, v82, v83
	v_cvt_pk_bf16_f32 v82, v84, v85
	v_cvt_pk_bf16_f32 v83, v86, v87
	v_cvt_pk_bf16_f32 v84, v88, v89
	v_mfma_f32_32x32x16_bf16 v[112:127], v[220:223], v[174:177], v[112:127]
	v_cvt_pk_bf16_f32 v85, v90, v91
	v_cvt_pk_bf16_f32 v86, v92, v93
	v_cvt_pk_bf16_f32 v87, v94, v95
	s_waitcnt vmcnt(0)
	s_barrier
	s_cmpk_gt_u32 s27, 0x81
	s_cbranch_scc1 .Lat_dma_endL
	s_cmp_lt_u32 s27, 2
	s_cselect_b32 s14, s10, s11
	s_add_i32 s14, s14, s24
	s_and_b64 vcc, exec, s[4:5]
	s_cbranch_vccnz .Lat_dmaL_0
	v_mad_u64_u32 v[234:235], s[16:17], v182, s14, v[180:181]
	s_add_i32 m0, s25, s19
	s_nop 0
	global_load_lds_dwordx4 v[234:235], off

; #define LAS __attribute__((address_space(3)))
; __device__ __forceinline__ void attn_unit2(LAS unsigned char* lds, const bf16_t* __restrict__ Q, const bf16_t* __restrict__ KN, const bf16_t* __restrict__ KPE, ...
;     ...
;         for (int ds = 0; ds < 6; ++ds) {
;             const bf16x8 k0 = *(const LAS bf16x8*)(ka + ds * 32);
;             const bf16x8 k1 = *(const LAS bf16x8*)(ka + 32 * KROW + ds * 32);
;             sa0 = __builtin_amdgcn_mfma_f32_32x32x16_bf16(k0, qa[ds], sa0, 0, 0, 0);
;             sa1 = __builtin_amdgcn_mfma_f32_32x32x16_bf16(k1, qa[ds], sa1, 0, 0, 0);
;             sb0 = __builtin_amdgcn_mfma_f32_32x32x16_bf16(k0, qb[ds], sb0, 0, 0, 0);
;             sb1 = __builtin_amdgcn_mfma_f32_32x32x16_bf16(k1, qb[ds], sb1, 0, 0, 0);
;         }
.Lat_dmaL_2:
.Lat_dma_endL:
	v_add3_u32 v224, s26, v183, v128
	ds_read_b128 v[212:215], v224 offset:0
	ds_read_b128 v[216:219], v224 offset:32
	ds_read_b128 v[220:223], v224 offset:64
	v_mfma_f32_32x32x16_bf16 v[16:31], v[196:199], v[64:67], v[16:31]
	v_sub_f32_e32 v96, v96, v194
	v_sub_f32_e32 v97, v97, v194
	v_sub_f32_e32 v98, v98, v194
	v_sub_f32_e32 v99, v99, v194
	v_mfma_f32_32x32x16_bf16 v[48:63], v[200:203], v[64:67], v[48:63]
	v_exp_f32_e32 v96, v96
	v_exp_f32_e32 v97, v97
	v_sub_f32_e32 v100, v100, v194
	v_sub_f32_e32 v101, v101, v194
	v_mfma_f32_32x32x16_bf16 v[16:31], v[204:207], v[68:71], v[16:31]
	v_exp_f32_e32 v98, v98
	v_exp_f32_e32 v99, v99
	v_sub_f32_e32 v102, v102, v194
	v_sub_f32_e32 v103, v103, v194
	v_mfma_f32_32x32x16_bf16 v[48:63], v[208:211], v[68:71], v[48:63]
	v_exp_f32_e32 v100, v100
	v_exp_f32_e32 v101, v101
	v_add_f32_e32 v230, v96, v97
	v_sub_f32_e32 v104, v104, v194
	v_sub_f32_e32 v105, v105, v194
	v_exp_f32_e32 v102, v102
	v_mfma_f32_32x32x16_bf16 v[32:47], v[196:199], v[80:83], v[32:47]
	v_exp_f32_e32 v103, v103
	v_add_f32_e32 v231, v98, v99
	v_sub_f32_e32 v106, v106, v194
	v_sub_f32_e32 v107, v107, v194
	v_mfma_f32_32x32x16_bf16 v[0:15], v[200:203], v[80:83], v[0:15]
	v_exp_f32_e32 v104, v104
	v_exp_f32_e32 v105, v105
	v_add_f32_e32 v230, v230, v100
	v_add_f32_e32 v231, v231, v101
	v_mfma_f32_32x32x16_bf16 v[32:47], v[204:207], v[84:87], v[32:47]
	v_sub_f32_e32 v108, v108, v194
	v_sub_f32_e32 v109, v109, v194
	v_exp_f32_e32 v106, v106
	v_exp_f32_e32 v107, v107
	v_mfma_f32_32x32x16_bf16 v[0:15], v[208:211], v[84:87], v[0:15]
	v_add_f32_e32 v230, v230, v102
	v_add3_u32 v225, s34, v187, v128
	ds_read_b128 v[196:199], v225 offset:13376
	ds_read_b128 v[200:203], v225 offset:17984
	ds_read_b128 v[204:207], v225 offset:13408
	ds_read_b128 v[208:211], v225 offset:18016
	v_add_f32_e32 v231, v231, v103
	v_sub_f32_e32 v110, v110, v194
	v_sub_f32_e32 v111, v111, v194
	v_exp_f32_e32 v108, v108
	v_exp_f32_e32 v109, v109
	v_add_f32_e32 v230, v230, v104
	v_add_f32_e32 v231, v231, v105
	v_exp_f32_e32 v110, v110
	v_exp_f32_e32 v111, v111
	v_add_f32_e32 v230, v230, v106
	v_add_f32_e32 v231, v231, v107
	v_add_f32_e32 v230, v230, v108
	v_add_f32_e32 v231, v231, v109
	v_add_f32_e32 v230, v230, v110
	v_add_f32_e32 v231, v231, v111
	v_add_f32_e32 v230, v230, v231
	v_cmp_lt_f32_e32 vcc, 0x45800000, v230
	s_cbranch_vccnz .Lat_resc_aO
.Lat_back_aO:
	v_add_f32_e32 v191, v191, v230
	s_waitcnt lgkmcnt(6)
	v_mfma_f32_32x32x16_bf16 v[64:79], v[212:215], v[130:133], 0
	v_cvt_pk_bf16_f32 v96, v96, v97
	v_cvt_pk_bf16_f32 v97, v98, v99
	v_cvt_pk_bf16_f32 v98, v100, v101
	v_cvt_pk_bf16_f32 v99, v102, v103
	v_cvt_pk_bf16_f32 v100, v104, v105
	v_cvt_pk_bf16_f32 v101, v106, v107
	v_mfma_f32_32x32x16_bf16 v[80:95], v[212:215], v[138:141], 0
	ds_read_b128 v[212:215], v224 offset:96
	v_cvt_pk_bf16_f32 v102, v108, v109
	v_cvt_pk_bf16_f32 v103, v110, v111
	v_sub_f32_e32 v112, v112, v195
	v_sub_f32_e32 v113, v113, v195
	v_sub_f32_e32 v114, v114, v195
	s_waitcnt lgkmcnt(6)
	v_mfma_f32_32x32x16_bf16 v[64:79], v[216:219], v[134:137], v[64:79]
	v_sub_f32_e32 v115, v115, v195
	v_exp_f32_e32 v112, v112
	v_exp_f32_e32 v113, v113
	v_sub_f32_e32 v116, v116, v195
	v_sub_f32_e32 v117, v117, v195
	v_exp_f32_e32 v114, v114
	v_mfma_f32_32x32x16_bf16 v[80:95], v[216:219], v[142:145], v[80:95]
	ds_read_b128 v[216:219], v224 offset:128
	v_exp_f32_e32 v115, v115
	v_sub_f32_e32 v118, v118, v195
	v_sub_f32_e32 v119, v119, v195
	v_exp_f32_e32 v116, v116
	v_exp_f32_e32 v117, v117
	v_add_f32_e32 v230, v112, v113
	s_waitcnt lgkmcnt(6)
	v_mfma_f32_32x32x16_bf16 v[64:79], v[220:223], v[146:149], v[64:79]
	v_sub_f32_e32 v120, v120, v195
	v_sub_f32_e32 v121, v121, v195
	v_exp_f32_e32 v118, v118
	v_exp_f32_e32 v119, v119
	v_add_f32_e32 v231, v114, v115
	v_mfma_f32_32x32x16_bf16 v[80:95], v[220:223], v[154:157], v[80:95]
	ds_read_b128 v[220:223], v224 offset:160
	v_sub_f32_e32 v122, v122, v195
	v_sub_f32_e32 v123, v123, v195
	v_exp_f32_e32 v120, v120
	v_exp_f32_e32 v121, v121
	v_add_f32_e32 v230, v230, v116
	v_add_f32_e32 v231, v231, v117
	s_waitcnt lgkmcnt(2)
	v_mfma_f32_32x32x16_bf16 v[64:79], v[212:215], v[150:153], v[64:79]
	v_sub_f32_e32 v124, v124, v195
	v_sub_f32_e32 v125, v125, v195
	v_exp_f32_e32 v122, v122
	v_exp_f32_e32 v123, v123
	v_add_f32_e32 v230, v230, v118
	v_mfma_f32_32x32x16_bf16 v[80:95], v[212:215], v[158:161], v[80:95]
	v_add_f32_e32 v231, v231, v119
	v_sub_f32_e32 v126, v126, v195
	v_sub_f32_e32 v127, v127, v195
	v_exp_f32_e32 v124, v124
	v_exp_f32_e32 v125, v125
	v_add_f32_e32 v230, v230, v120
	s_waitcnt lgkmcnt(1)
	v_mfma_f32_32x32x16_bf16 v[64:79], v[216:219], v[162:165], v[64:79]
	v_add_f32_e32 v231, v231, v121
	v_exp_f32_e32 v126, v126
	v_exp_f32_e32 v127, v127
	v_add_f32_e32 v230, v230, v122
	v_add_f32_e32 v231, v231, v123
	v_add_f32_e32 v230, v230, v124
	v_mfma_f32_32x32x16_bf16 v[80:95], v[216:219], v[170:173], v[80:95]
	v_add_f32_e32 v231, v231, v125
	v_add_f32_e32 v230, v230, v126
	v_add_f32_e32 v231, v231, v127
	v_add_f32_e32 v230, v230, v231
	v_cmp_lt_f32_e32 vcc, 0x45800000, v230
	s_cbranch_vccnz .Lat_resc_bO
; #define LAS __attribute__((address_space(3)))
; __device__ __forceinline__ void attn_unit2(LAS unsigned char* lds, const bf16_t* __restrict__ Q, const bf16_t* __restrict__ KN, const bf16_t* __restrict__ KPE, ...
;     ...
; #pragma unroll
;         for (int st = 0; st < 4; ++st) {
;             const bf16x8 v0 = *(const LAS bf16x8*)(va + st * 32);
;             const bf16x8 v1 = *(const LAS bf16x8*)(va + 32 * VROW + st * 32);
;             const bf16x8 fa = __builtin_bit_cast(bf16x8, pa[st]), fb = __builtin_bit_cast(bf16x8, pb[st]);
;             oa0 = __builtin_amdgcn_mfma_f32_32x32x16_bf16(v0, fa, oa0, 0, 0, 0);
;             oa1 = __builtin_amdgcn_mfma_f32_32x32x16_bf16(v1, fa, oa1, 0, 0, 0);
;             ob0 = __builtin_amdgcn_mfma_f32_32x32x16_bf16(v0, fb, ob0, 0, 0, 0);
;             ob1 = __builtin_amdgcn_mfma_f32_32x32x16_bf16(v1, fb, ob1, 0, 0, 0);
;         }
;         __builtin_amdgcn_sched_barrier(0);
;         __syncthreads();
;         { const int tmp = sc; sc = sn; sn = snn; snn = tmp; }
.Lat_back_bO:
	s_waitcnt lgkmcnt(0)
	v_mfma_f32_32x32x16_bf16 v[64:79], v[220:223], v[166:169], v[64:79]
	v_add_f32_e32 v193, v193, v230
	v_cvt_pk_bf16_f32 v112, v112, v113
	v_cvt_pk_bf16_f32 v113, v114, v115
	v_cvt_pk_bf16_f32 v114, v116, v117
	v_cvt_pk_bf16_f32 v115, v118, v119
	v_cvt_pk_bf16_f32 v116, v120, v121
	v_mfma_f32_32x32x16_bf16 v[80:95], v[220:223], v[174:177], v[80:95]
	v_cvt_pk_bf16_f32 v117, v122, v123
	v_cvt_pk_bf16_f32 v118, v124, v125
	v_cvt_pk_bf16_f32 v119, v126, v127
	s_add_i32 s27, s27, 1
	s_add_i32 s24, s24, 64
	s_mov_b32 s14, s34
	s_mov_b32 s34, s26
	s_mov_b32 s26, s25
	s_mov_b32 s25, s14
	s_cmpk_lg_i32 s27, 0x84
	s_cbranch_scc1 .Lat_loop
	s_waitcnt lgkmcnt(3)
	v_mfma_f32_32x32x16_bf16 v[16:31], v[196:199], v[96:99], v[16:31]
	s_waitcnt lgkmcnt(2)
	v_mfma_f32_32x32x16_bf16 v[48:63], v[200:203], v[96:99], v[48:63]
	s_waitcnt lgkmcnt(1)
	v_mfma_f32_32x32x16_bf16 v[16:31], v[204:207], v[100:103], v[16:31]
	s_waitcnt lgkmcnt(0)
	v_mfma_f32_32x32x16_bf16 v[48:63], v[208:211], v[100:103], v[48:63]
	v_mfma_f32_32x32x16_bf16 v[32:47], v[196:199], v[112:115], v[32:47]
	v_mfma_f32_32x32x16_bf16 v[0:15], v[200:203], v[112:115], v[0:15]
	v_mfma_f32_32x32x16_bf16 v[32:47], v[204:207], v[116:119], v[32:47]
	v_mfma_f32_32x32x16_bf16 v[0:15], v[208:211], v[116:119], v[0:15]
	s_branch .Lat_done
.Lat_resc_aE:
	s_nop 15
	v_max3_f32 v226, v64, v65, v66
	v_max3_f32 v227, v67, v68, v69
	v_max3_f32 v226, v226, v70, v71
	v_max3_f32 v227, v227, v72, v73
	v_max3_f32 v226, v226, v74, v75
	v_max3_f32 v227, v227, v76, v77
	v_max3_f32 v226, v226, v78, v79
	v_max_f32_e32 v226, v226, v227
	v_mov_b32_e32 v227, v226
	s_nop 1
	v_permlane32_swap_b32_e32 v226, v227
	v_max_f32_e32 v226, v226, v227
	v_max_f32_e32 v226, 1.0, v226
	v_log_f32_e32 v226, v226
	s_nop 0
	v_add_f32_e32 v227, v194, v226
	v_cvt_pk_bf16_f32 v227, v227, v227
	v_and_b32_e32 v227, 0xffff0000, v227
	v_sub_f32_e32 v229, v194, v227
	v_mov_b32_e32 v194, v227
	v_exp_f32_e32 v232, v229
	v_mul_f32_e32 v64, v64, v232
	v_mul_f32_e32 v65, v65, v232
	v_mul_f32_e32 v66, v66, v232
	v_mul_f32_e32 v67, v67, v232
	v_mul_f32_e32 v68, v68, v232
	v_mul_f32_e32 v69, v69, v232
	v_mul_f32_e32 v70, v70, v232
	v_mul_f32_e32 v71, v71, v232
	v_mul_f32_e32 v72, v72, v232
	v_mul_f32_e32 v73, v73, v232
	v_mul_f32_e32 v74, v74, v232
	v_mul_f32_e32 v75, v75, v232
	v_mul_f32_e32 v76, v76, v232
	v_mul_f32_e32 v77, v77, v232
	v_mul_f32_e32 v78, v78, v232
	v_mul_f32_e32 v79, v79, v232
	v_mul_f32_e32 v230, v230, v232
	v_pk_mul_f32 v[16:17], v[16:17], v[232:233] op_sel_hi:[1,0]
	v_pk_mul_f32 v[18:19], v[18:19], v[232:233] op_sel_hi:[1,0]
	v_pk_mul_f32 v[20:21], v[20:21], v[232:233] op_sel_hi:[1,0]
	v_pk_mul_f32 v[22:23], v[22:23], v[232:233] op_sel_hi:[1,0]
	v_pk_mul_f32 v[24:25], v[24:25], v[232:233] op_sel_hi:[1,0]
	v_pk_mul_f32 v[26:27], v[26:27], v[232:233] op_sel_hi:[1,0]
	v_pk_mul_f32 v[28:29], v[28:29], v[232:233] op_sel_hi:[1,0]
	v_pk_mul_f32 v[30:31], v[30:31], v[232:233] op_sel_hi:[1,0]
	v_pk_mul_f32 v[48:49], v[48:49], v[232:233] op_sel_hi:[1,0]
	v_pk_mul_f32 v[50:51], v[50:51], v[232:233] op_sel_hi:[1,0]
	v_pk_mul_f32 v[52:53], v[52:53], v[232:233] op_sel_hi:[1,0]
	v_pk_mul_f32 v[54:55], v[54:55], v[232:233] op_sel_hi:[1,0]
	v_pk_mul_f32 v[56:57], v[56:57], v[232:233] op_sel_hi:[1,0]
	v_pk_mul_f32 v[58:59], v[58:59], v[232:233] op_sel_hi:[1,0]
	v_pk_mul_f32 v[60:61], v[60:61], v[232:233] op_sel_hi:[1,0]
	v_pk_mul_f32 v[62:63], v[62:63], v[232:233] op_sel_hi:[1,0]
	v_mul_f32_e32 v191, v191, v232
	s_branch .Lat_back_aE
.Lat_resc_bE:
	s_nop 15
	v_max3_f32 v236, v80, v81, v82
	v_max3_f32 v237, v83, v84, v85
	v_max3_f32 v236, v236, v86, v87
	v_max3_f32 v237, v237, v88, v89
	v_max3_f32 v236, v236, v90, v91
	v_max3_f32 v237, v237, v92, v93
	v_max3_f32 v236, v236, v94, v95
	v_max_f32_e32 v236, v236, v237
	v_mov_b32_e32 v237, v236
	s_nop 1
	v_permlane32_swap_b32_e32 v236, v237
	v_max_f32_e32 v236, v236, v237
	v_max_f32_e32 v236, 1.0, v236
	v_log_f32_e32 v236, v236
	s_nop 0
	v_add_f32_e32 v237, v195, v236
	v_cvt_pk_bf16_f32 v237, v237, v237
	v_and_b32_e32 v237, 0xffff0000, v237
	v_sub_f32_e32 v229, v195, v237
	v_mov_b32_e32 v195, v237
	v_exp_f32_e32 v232, v229
	v_mul_f32_e32 v80, v80, v232
	v_mul_f32_e32 v81, v81, v232
	v_mul_f32_e32 v82, v82, v232
	v_mul_f32_e32 v83, v83, v232
	v_mul_f32_e32 v84, v84, v232
	v_mul_f32_e32 v85, v85, v232
	v_mul_f32_e32 v86, v86, v232
	v_mul_f32_e32 v87, v87, v232
	v_mul_f32_e32 v88, v88, v232
	v_mul_f32_e32 v89, v89, v232
	v_mul_f32_e32 v90, v90, v232
	v_mul_f32_e32 v91, v91, v232
	v_mul_f32_e32 v92, v92, v232
	v_mul_f32_e32 v93, v93, v232
	v_mul_f32_e32 v94, v94, v232
	v_mul_f32_e32 v95, v95, v232
	v_mul_f32_e32 v230, v230, v232
	v_pk_mul_f32 v[32:33], v[32:33], v[232:233] op_sel_hi:[1,0]
	v_pk_mul_f32 v[34:35], v[34:35], v[232:233] op_sel_hi:[1,0]
	v_pk_mul_f32 v[36:37], v[36:37], v[232:233] op_sel_hi:[1,0]
	v_pk_mul_f32 v[38:39], v[38:39], v[232:233] op_sel_hi:[1,0]
	v_pk_mul_f32 v[40:41], v[40:41], v[232:233] op_sel_hi:[1,0]
	v_pk_mul_f32 v[42:43], v[42:43], v[232:233] op_sel_hi:[1,0]
	v_pk_mul_f32 v[44:45], v[44:45], v[232:233] op_sel_hi:[1,0]
	v_pk_mul_f32 v[46:47], v[46:47], v[232:233] op_sel_hi:[1,0]
	v_pk_mul_f32 v[0:1], v[0:1], v[232:233] op_sel_hi:[1,0]
	v_pk_mul_f32 v[2:3], v[2:3], v[232:233] op_sel_hi:[1,0]
	v_pk_mul_f32 v[4:5], v[4:5], v[232:233] op_sel_hi:[1,0]
	v_pk_mul_f32 v[6:7], v[6:7], v[232:233] op_sel_hi:[1,0]
	v_pk_mul_f32 v[8:9], v[8:9], v[232:233] op_sel_hi:[1,0]
	v_pk_mul_f32 v[10:11], v[10:11], v[232:233] op_sel_hi:[1,0]
	v_pk_mul_f32 v[12:13], v[12:13], v[232:233] op_sel_hi:[1,0]
	v_pk_mul_f32 v[14:15], v[14:15], v[232:233] op_sel_hi:[1,0]
	v_mul_f32_e32 v193, v193, v232
	s_branch .Lat_back_bE
.Lat_resc_aO:
	s_nop 15
	v_max3_f32 v226, v96, v97, v98
	v_max3_f32 v227, v99, v100, v101
	v_max3_f32 v226, v226, v102, v103
	v_max3_f32 v227, v227, v104, v105
	v_max3_f32 v226, v226, v106, v107
	v_max3_f32 v227, v227, v108, v109
	v_max3_f32 v226, v226, v110, v111
	v_max_f32_e32 v226, v226, v227
	v_mov_b32_e32 v227, v226
	s_nop 1
	v_permlane32_swap_b32_e32 v226, v227
	v_max_f32_e32 v226, v226, v227
	v_max_f32_e32 v226, 1.0, v226
	v_log_f32_e32 v226, v226
	s_nop 0
	v_add_f32_e32 v227, v194, v226
	v_cvt_pk_bf16_f32 v227, v227, v227
	v_and_b32_e32 v227, 0xffff0000, v227
	v_sub_f32_e32 v229, v194, v227
	v_mov_b32_e32 v194, v227
	v_exp_f32_e32 v232, v229
	v_mul_f32_e32 v96, v96, v232
	v_mul_f32_e32 v97, v97, v232
	v_mul_f32_e32 v98, v98, v232
	v_mul_f32_e32 v99, v99, v232
	v_mul_f32_e32 v100, v100, v232
	v_mul_f32_e32 v101, v101, v232
	v_mul_f32_e32 v102, v102, v232
	v_mul_f32_e32 v103, v103, v232
	v_mul_f32_e32 v104, v104, v232
	v_mul_f32_e32 v105, v105, v232
	v_mul_f32_e32 v106, v106, v232
	v_mul_f32_e32 v107, v107, v232
	v_mul_f32_e32 v108, v108, v232
	v_mul_f32_e32 v109, v109, v232
	v_mul_f32_e32 v110, v110, v232
	v_mul_f32_e32 v111, v111, v232
	v_mul_f32_e32 v230, v230, v232
	v_pk_mul_f32 v[16:17], v[16:17], v[232:233] op_sel_hi:[1,0]
	v_pk_mul_f32 v[18:19], v[18:19], v[232:233] op_sel_hi:[1,0]
	v_pk_mul_f32 v[20:21], v[20:21], v[232:233] op_sel_hi:[1,0]
	v_pk_mul_f32 v[22:23], v[22:23], v[232:233] op_sel_hi:[1,0]
	v_pk_mul_f32 v[24:25], v[24:25], v[232:233] op_sel_hi:[1,0]
	v_pk_mul_f32 v[26:27], v[26:27], v[232:233] op_sel_hi:[1,0]
	v_pk_mul_f32 v[28:29], v[28:29], v[232:233] op_sel_hi:[1,0]
	v_pk_mul_f32 v[30:31], v[30:31], v[232:233] op_sel_hi:[1,0]
	v_pk_mul_f32 v[48:49], v[48:49], v[232:233] op_sel_hi:[1,0]
	v_pk_mul_f32 v[50:51], v[50:51], v[232:233] op_sel_hi:[1,0]
	v_pk_mul_f32 v[52:53], v[52:53], v[232:233] op_sel_hi:[1,0]
	v_pk_mul_f32 v[54:55], v[54:55], v[232:233] op_sel_hi:[1,0]
	v_pk_mul_f32 v[56:57], v[56:57], v[232:233] op_sel_hi:[1,0]
	v_pk_mul_f32 v[58:59], v[58:59], v[232:233] op_sel_hi:[1,0]
	v_pk_mul_f32 v[60:61], v[60:61], v[232:233] op_sel_hi:[1,0]
	v_pk_mul_f32 v[62:63], v[62:63], v[232:233] op_sel_hi:[1,0]
	v_mul_f32_e32 v191, v191, v232
	s_branch .Lat_back_aO
.Lat_resc_bO:
	s_nop 15
	v_max3_f32 v236, v112, v113, v114
	v_max3_f32 v237, v115, v116, v117
	v_max3_f32 v236, v236, v118, v119
	v_max3_f32 v237, v237, v120, v121
	v_max3_f32 v236, v236, v122, v123
	v_max3_f32 v237, v237, v124, v125
	v_max3_f32 v236, v236, v126, v127
	v_max_f32_e32 v236, v236, v237
	v_mov_b32_e32 v237, v236
	s_nop 1
	v_permlane32_swap_b32_e32 v236, v237
	v_max_f32_e32 v236, v236, v237
	v_max_f32_e32 v236, 1.0, v236
	v_log_f32_e32 v236, v236
	s_nop 0
	v_add_f32_e32 v237, v195, v236
	v_cvt_pk_bf16_f32 v237, v237, v237
	v_and_b32_e32 v237, 0xffff0000, v237
	v_sub_f32_e32 v229, v195, v237
	v_mov_b32_e32 v195, v237
	v_exp_f32_e32 v232, v229
	v_mul_f32_e32 v112, v112, v232
	v_mul_f32_e32 v113, v113, v232
	v_mul_f32_e32 v114, v114, v232
	v_mul_f32_e32 v115, v115, v232
	v_mul_f32_e32 v116, v116, v232
	v_mul_f32_e32 v117, v117, v232
	v_mul_f32_e32 v118, v118, v232
	v_mul_f32_e32 v119, v119, v232
	v_mul_f32_e32 v120, v120, v232
	v_mul_f32_e32 v121, v121, v232
	v_mul_f32_e32 v122, v122, v232
	v_mul_f32_e32 v123, v123, v232
	v_mul_f32_e32 v124, v124, v232
	v_mul_f32_e32 v125, v125, v232
	v_mul_f32_e32 v126, v126, v232
	v_mul_f32_e32 v127, v127, v232
	v_mul_f32_e32 v230, v230, v232
	v_pk_mul_f32 v[32:33], v[32:33], v[232:233] op_sel_hi:[1,0]
	v_pk_mul_f32 v[34:35], v[34:35], v[232:233] op_sel_hi:[1,0]
	v_pk_mul_f32 v[36:37], v[36:37], v[232:233] op_sel_hi:[1,0]
	v_pk_mul_f32 v[38:39], v[38:39], v[232:233] op_sel_hi:[1,0]
	v_pk_mul_f32 v[40:41], v[40:41], v[232:233] op_sel_hi:[1,0]
	v_pk_mul_f32 v[42:43], v[42:43], v[232:233] op_sel_hi:[1,0]
	v_pk_mul_f32 v[44:45], v[44:45], v[232:233] op_sel_hi:[1,0]
	v_pk_mul_f32 v[46:47], v[46:47], v[232:233] op_sel_hi:[1,0]
	v_pk_mul_f32 v[0:1], v[0:1], v[232:233] op_sel_hi:[1,0]
	v_pk_mul_f32 v[2:3], v[2:3], v[232:233] op_sel_hi:[1,0]
	v_pk_mul_f32 v[4:5], v[4:5], v[232:233] op_sel_hi:[1,0]
	v_pk_mul_f32 v[6:7], v[6:7], v[232:233] op_sel_hi:[1,0]
	v_pk_mul_f32 v[8:9], v[8:9], v[232:233] op_sel_hi:[1,0]
	v_pk_mul_f32 v[10:11], v[10:11], v[232:233] op_sel_hi:[1,0]
	v_pk_mul_f32 v[12:13], v[12:13], v[232:233] op_sel_hi:[1,0]
	v_pk_mul_f32 v[14:15], v[14:15], v[232:233] op_sel_hi:[1,0]
	v_mul_f32_e32 v193, v193, v232
	s_branch .Lat_back_bO
